# movpk: accumulator hand-over at loop bottoms with v_pk_mov_b32 pairs
# speedup vs baseline: 1.0233x; 1.0086x over previous
.Lsel_skip_pf:
	s_waitcnt lgkmcnt(0)
	s_barrier
	s_mov_b32 s32, s89
	s_mov_b32 s97, s91
	s_mov_b32 s89, s98
	s_mov_b32 s91, s99
	s_add_i32 s0, s83, 2
	s_add_i32 s1, s83, -2
	s_cmp_lt_u32 s1, s79
	s_cbranch_scc0 .LBB0_1051
	v_mov_b64_e32 v[32:33], v[80:81]
	s_mov_b32 s83, s0
	v_mov_b64_e32 v[34:35], v[82:83]
	v_pk_mov_b32 v[36:37], v[0:1], v[0:1] op_sel:[0,1]
	v_pk_mov_b32 v[38:39], v[2:3], v[2:3] op_sel:[0,1]
	v_pk_mov_b32 v[40:41], v[4:5], v[4:5] op_sel:[0,1]
	v_pk_mov_b32 v[42:43], v[6:7], v[6:7] op_sel:[0,1]
	v_pk_mov_b32 v[44:45], v[8:9], v[8:9] op_sel:[0,1]
	v_pk_mov_b32 v[46:47], v[10:11], v[10:11] op_sel:[0,1]
	v_pk_mov_b32 v[84:85], v[12:13], v[12:13] op_sel:[0,1]
	v_pk_mov_b32 v[86:87], v[14:15], v[14:15] op_sel:[0,1]
	s_branch .LBB0_1040

.Lwin_skip_pf:
	s_waitcnt lgkmcnt(0)
	s_barrier
	s_add_i32 s1, s23, 2
	s_add_i32 s23, s23, -3
	s_cmp_lt_i32 s23, s21
	v_add_u32_e32 v81, 0xffffff80, v81
	s_cbranch_scc0 .LBB0_1069
	v_mov_b64_e32 v[88:89], v[84:85]
	s_mov_b32 s24, s0
	s_mov_b32 s23, s1
	v_mov_b64_e32 v[86:87], v[82:83]
	v_pk_mov_b32 v[90:91], v[16:17], v[16:17] op_sel:[0,1]
	v_pk_mov_b32 v[92:93], v[18:19], v[18:19] op_sel:[0,1]
	v_pk_mov_b32 v[94:95], v[20:21], v[20:21] op_sel:[0,1]
	v_pk_mov_b32 v[96:97], v[22:23], v[22:23] op_sel:[0,1]
	v_pk_mov_b32 v[98:99], v[24:25], v[24:25] op_sel:[0,1]
	v_pk_mov_b32 v[100:101], v[26:27], v[26:27] op_sel:[0,1]
	v_pk_mov_b32 v[102:103], v[28:29], v[28:29] op_sel:[0,1]
	v_pk_mov_b32 v[104:105], v[30:31], v[30:31] op_sel:[0,1]
	s_branch .LBB0_1061
